# combined: 96 designated conversion workgroups + pipelined FFN-down epilogue + DPP/permlane LayerNorm reductions + padded-table attention bias loads
# speedup vs baseline: 1.0011x; 1.0011x over previous
; __device__ __forceinline__ int oi(int k) { asm volatile("" : "+s"(k)); return k; }
; __device__ __forceinline__ const float* gfp(const float* p) { ASSUME_GLOBAL(p); return p; }
; __global__ void __launch_bounds__(512, 2) mega_fwd(Args a) {
;     ...
;                     if (tid < 128) { const float* rbias = gfp(a.in[oi(1)]); ((float*)(lds_raw + att::LDS_BIAS))[tid] = (rbias[a.bucket[tid] * 4 + hh] - rbias[31 * 4 + hh]) * LOG2E; }
;                     __syncthreads();
.LBB0_684:
	s_or_b64 exec, exec, s[2:3]
	v_cmp_lt_u32_e32 vcc, 127, v166
	s_and_saveexec_b64 s[4:5], vcc
	v_mov_b32_e32 v0, 0
	v_lshl_add_u32 v2, v166, 2, s33
	ds_write_b32 v2, v0
	s_or_b64 exec, exec, s[4:5]
	s_and_b32 s6, s40, 1
	s_mov_b64 s[96:97], 0
	s_cmp_eq_u32 s6, 0
	s_mov_b64 s[2:3], -1
	s_waitcnt lgkmcnt(0)
	s_barrier
	s_cbranch_scc1 .LBB0_686
	s_mov_b64 s[24:25], 0
	s_mov_b64 s[2:3], 0

; __device__ __forceinline__ void finishSM(f32x16& p0, f32x16& p1, float alpha, float& l_reg, bf16x8& pa0, bf16x8& pa1, bf16x8& pa2, bf16x8& pa3) {
; #pragma unroll
;     for (int r = 0; r < 16; ++r) p1[r] = __builtin_amdgcn_exp2f(p1[r]);
;     float ps = 0;
; #pragma unroll
;     for (int r = 0; r < 16; ++r) ps += p0[r];
; #pragma unroll
;     for (int r = 0; r < 16; ++r) ps += p1[r];
;     { auto rr = __builtin_amdgcn_permlane32_swap(__float_as_uint(ps), __float_as_uint(ps), false, false);
;       ps = __uint_as_float(rr[0]) + __uint_as_float(rr[1]); }
;     l_reg = l_reg * alpha + ps;
;     ...
;     PK4(p0, 0, pa0); PK4(p0, 8, pa1); PK4(p1, 0, pa2); PK4(p1, 8, pa3);
;     ...
; }
; template <int KB, int DQK>
; __device__ __forceinline__ void qkt(f32x16& p0, f32x16& p1, const char* K_lds, int r32, int hi, const bf16x8* qr, const char* qrl) {
;     constexpr int SHMK = 64 * DQK * 2, NF = DQK / 16, NFR = NF > 8 ? 8 : NF;
;     p0 = f32x16{}; p1 = f32x16{};
;     const char* kb[4];
; #pragma unroll
;     for (int dd = 0; dd < 4; ++dd) kb[dd] = K_lds + KB * SHMK + kswz<DQK>(r32, (dd * 16 + hi * 8) * 2);
; #pragma unroll
;     for (int d0 = 0; d0 < NF; ++d0) { const char* a = kb[d0 & 3] + (d0 >> 2) * 128;
;         bf16x8 b0 = *reinterpret_cast<const bf16x8*>(a);
;         bf16x8 b1 = *reinterpret_cast<const bf16x8*>(a + 32 * DQK * 2);
;         bf16x8 q; if (d0 < NFR) q = qr[d0]; else q = *reinterpret_cast<const bf16x8*>(qrl + (d0 - NFR) * 1024);
;         p0 = __builtin_amdgcn_mfma_f32_32x32x16_bf16(b0, q, p0, 0, 0, 0);
;         p1 = __builtin_amdgcn_mfma_f32_32x32x16_bf16(b1, q, p1, 0, 0, 0); }
; }
; template <int VB>
; __device__ __forceinline__ void pv_tile(f32x16* o, int vb0, bf16x8 pa0, bf16x8 pa1, bf16x8 pa2, bf16x8 pa3) {
;     ...
;     PV_D0(0); PV_D0(1); PV_D0(2); PV_D0(3);
;     ...
; }
.LBB0_693:
	ds_read_b128 v[66:69], v161 offset:40960
	ds_read_b128 v[70:73], v161 offset:45056
	v_add_f32_e32 v0, 0, v149
	v_add_f32_e32 v0, v186, v0
	v_add_f32_e32 v0, v147, v0
	s_waitcnt lgkmcnt(1)
	v_mfma_f32_32x32x16_bf16 v[82:97], v[66:69], v[110:113], 0
	v_add_f32_e32 v0, v183, v0
	v_add_f32_e32 v0, v141, v0
	ds_read_b128 v[188:191], v162 offset:40960
	ds_read_b128 v[192:195], v162 offset:45056
	v_add_f32_e32 v0, v148, v0
	v_add_f32_e32 v0, v140, v0
	v_add_f32_e32 v0, v146, v0
	v_add_f32_e32 v0, v137, v0
	s_waitcnt lgkmcnt(2)
	v_mfma_f32_32x32x16_bf16 v[66:81], v[70:73], v[110:113], 0
	v_add_f32_e32 v0, v139, v0
	v_add_f32_e32 v0, v135, v0
	v_add_f32_e32 v0, v138, v0
	v_exp_f32_e32 v122, v122
	v_add_f32_e32 v0, v133, v0
	v_exp_f32_e32 v123, v123
	v_add_f32_e32 v0, v136, v0
	s_waitcnt lgkmcnt(1)
	v_mfma_f32_32x32x16_bf16 v[82:97], v[188:191], v[106:109], v[82:97]
	v_exp_f32_e32 v131, v126
	v_add_f32_e32 v0, v132, v0
	v_exp_f32_e32 v167, v127
	v_add_f32_e32 v0, v134, v0
	v_exp_f32_e32 v114, v114
	v_add_f32_e32 v0, v122, v0
	v_exp_f32_e32 v115, v115
	s_waitcnt lgkmcnt(0)
	v_mfma_f32_32x32x16_bf16 v[66:81], v[192:195], v[106:109], v[66:81]
	ds_read_b128 v[188:191], v163 offset:40960
	ds_read_b128 v[192:195], v163 offset:45056
	v_add_f32_e32 v0, v123, v0
	v_exp_f32_e32 v120, v120
	v_add_f32_e32 v0, v131, v0
	v_exp_f32_e32 v121, v121
	v_add_f32_e32 v0, v167, v0
	v_exp_f32_e32 v124, v124
	s_waitcnt lgkmcnt(1)
	v_mfma_f32_32x32x16_bf16 v[82:97], v[188:191], v[102:105], v[82:97]
	v_add_f32_e32 v0, v114, v0
	v_exp_f32_e32 v125, v125
	v_add_f32_e32 v0, v115, v0
	v_exp_f32_e32 v170, v128
	v_add_f32_e32 v0, v120, v0
	v_exp_f32_e32 v171, v129
	v_add_f32_e32 v0, v121, v0
	s_waitcnt lgkmcnt(0)
	v_mfma_f32_32x32x16_bf16 v[66:81], v[192:195], v[102:105], v[66:81]
	ds_read_b128 v[188:191], v164 offset:40960
	ds_read_b128 v[192:195], v164 offset:45056
	v_exp_f32_e32 v116, v116
	v_add_f32_e32 v0, v124, v0
	v_exp_f32_e32 v117, v117
	v_add_f32_e32 v0, v125, v0
	v_exp_f32_e32 v118, v118
	v_add_f32_e32 v0, v170, v0
	s_waitcnt lgkmcnt(1)
	v_mfma_f32_32x32x16_bf16 v[82:97], v[188:191], v[98:101], v[82:97]
	v_exp_f32_e32 v119, v119
	v_add_f32_e32 v0, v171, v0
	v_add_f32_e32 v0, v116, v0
	v_add_f32_e32 v0, v117, v0
	v_add_f32_e32 v0, v118, v0
	v_add_f32_e32 v0, v119, v0
	v_mov_b32_e32 v181, v0
	s_waitcnt lgkmcnt(0)
	v_mfma_f32_32x32x16_bf16 v[66:81], v[192:195], v[98:101], v[66:81]
	v_cvt_pk_bf16_f32 v126, v149, v186
	v_cvt_pk_bf16_f32 v127, v147, v183
	v_cvt_pk_bf16_f32 v128, v141, v148
	v_permlane32_swap_b32_e32 v0, v181
	v_cvt_pk_bf16_f32 v129, v140, v146
	v_permlane32_swap_b32_e32 v126, v128
	v_cvt_pk_bf16_f32 v182, v137, v139
	v_cvt_pk_bf16_f32 v183, v135, v138
	v_cvt_pk_bf16_f32 v184, v133, v136
	v_cvt_pk_bf16_f32 v185, v132, v134
	v_cvt_pk_bf16_f32 v132, v122, v123
	v_cvt_pk_bf16_f32 v133, v131, v167
	v_cvt_pk_bf16_f32 v134, v114, v115
	v_cvt_pk_bf16_f32 v135, v120, v121
	v_cvt_pk_bf16_f32 v136, v124, v125
	v_cvt_pk_bf16_f32 v137, v170, v171
	v_cvt_pk_bf16_f32 v138, v116, v117
	v_cvt_pk_bf16_f32 v139, v118, v119
	v_permlane32_swap_b32_e32 v127, v129
	v_permlane32_swap_b32_e32 v182, v184
	v_permlane32_swap_b32_e32 v183, v185
	v_permlane32_swap_b32_e32 v132, v134
	v_permlane32_swap_b32_e32 v133, v135
	v_permlane32_swap_b32_e32 v136, v138
	v_permlane32_swap_b32_e32 v137, v139
	v_lshl_add_u64 v[146:147], v[142:143], 0, s[26:27]
	v_add_co_u32_e32 v114, vcc, s20, v146
	s_mov_b32 s4, 0x18cb4000
	s_nop 0
	v_addc_co_u32_e32 v115, vcc, 0, v147, vcc
	v_add_co_u32_e32 v118, vcc, s4, v146
	v_lshl_add_u64 v[148:149], v[144:145], 0, s[26:27]
	s_nop 0
	v_addc_co_u32_e32 v119, vcc, 0, v147, vcc
	v_add_co_u32_e32 v122, vcc, s20, v148
	global_load_dwordx4 v[114:117], v[114:115], off offset:3456
	s_nop 0
	global_load_dwordx4 v[118:121], v[118:119], off offset:3456
	v_addc_co_u32_e32 v123, vcc, 0, v149, vcc
	global_load_dwordx4 v[122:125], v[122:123], off offset:2432
	ds_read_b64_tr_b16 v[186:187], v153 offset:0
	ds_read_b64_tr_b16 v[188:189], v153 offset:0x800
	ds_read_b64_tr_b16 v[190:191], v153 offset:0x1000
	ds_read_b64_tr_b16 v[192:193], v153 offset:0x1800
	ds_read_b64_tr_b16 v[194:195], v153 offset:0x2000
	ds_read_b64_tr_b16 v[196:197], v153 offset:0x2800
	ds_read_b64_tr_b16 v[208:209], v153 offset:0x3000
	ds_read_b64_tr_b16 v[210:211], v153 offset:0x3800
	s_waitcnt lgkmcnt(0)
	s_nop 0
	v_mfma_f32_32x32x16_bf16 v[50:65], v[126:129], v[186:189], v[50:65]
	ds_read_b64_tr_b16 v[186:187], v153 offset:0x200
	ds_read_b64_tr_b16 v[188:189], v153 offset:0xa00
	v_mfma_f32_32x32x16_bf16 v[50:65], v[182:185], v[190:193], v[50:65]
	ds_read_b64_tr_b16 v[190:191], v153 offset:0x1200
	ds_read_b64_tr_b16 v[192:193], v153 offset:0x1a00
	v_mfma_f32_32x32x16_bf16 v[50:65], v[132:135], v[194:197], v[50:65]
	ds_read_b64_tr_b16 v[194:195], v153 offset:0x2200
	ds_read_b64_tr_b16 v[196:197], v153 offset:0x2a00
	v_mfma_f32_32x32x16_bf16 v[50:65], v[136:139], v[208:211], v[50:65]
	ds_read_b64_tr_b16 v[208:209], v153 offset:0x3200
	ds_read_b64_tr_b16 v[210:211], v153 offset:0x3a00
	s_waitcnt lgkmcnt(0)
	v_mfma_f32_32x32x16_bf16 v[34:49], v[126:129], v[186:189], v[34:49]
	ds_read_b64_tr_b16 v[186:187], v153 offset:0x400
	ds_read_b64_tr_b16 v[188:189], v153 offset:0xc00
	v_mfma_f32_32x32x16_bf16 v[34:49], v[182:185], v[190:193], v[34:49]
	ds_read_b64_tr_b16 v[190:191], v153 offset:0x1400
	ds_read_b64_tr_b16 v[192:193], v153 offset:0x1c00
	v_mfma_f32_32x32x16_bf16 v[34:49], v[132:135], v[194:197], v[34:49]
	ds_read_b64_tr_b16 v[194:195], v153 offset:0x2400
	ds_read_b64_tr_b16 v[196:197], v153 offset:0x2c00
	v_mfma_f32_32x32x16_bf16 v[34:49], v[136:139], v[208:211], v[34:49]
	ds_read_b64_tr_b16 v[208:209], v153 offset:0x3400
	ds_read_b64_tr_b16 v[210:211], v153 offset:0x3c00
	s_waitcnt lgkmcnt(0)
	v_mfma_f32_32x32x16_bf16 v[18:33], v[126:129], v[186:189], v[18:33]
	ds_read_b64_tr_b16 v[186:187], v153 offset:0x600
	ds_read_b64_tr_b16 v[188:189], v153 offset:0xe00
	v_mfma_f32_32x32x16_bf16 v[18:33], v[182:185], v[190:193], v[18:33]
	ds_read_b64_tr_b16 v[190:191], v153 offset:0x1600
	ds_read_b64_tr_b16 v[192:193], v153 offset:0x1e00
	v_mfma_f32_32x32x16_bf16 v[18:33], v[132:135], v[194:197], v[18:33]
	ds_read_b64_tr_b16 v[194:195], v153 offset:0x2600
	ds_read_b64_tr_b16 v[196:197], v153 offset:0x2e00
	v_mfma_f32_32x32x16_bf16 v[18:33], v[136:139], v[208:211], v[18:33]
	ds_read_b64_tr_b16 v[208:209], v153 offset:0x3600
	ds_read_b64_tr_b16 v[210:211], v153 offset:0x3e00
	s_waitcnt lgkmcnt(0)
	v_mfma_f32_32x32x16_bf16 v[2:17], v[126:129], v[186:189], v[2:17]
	s_add_i32 s4, s21, 49
	s_cmp_le_i32 s4, s30
	v_add_u32_e32 v126, 0x5b, v180
	v_mfma_f32_32x32x16_bf16 v[2:17], v[182:185], v[190:193], v[2:17]
	v_mfma_f32_32x32x16_bf16 v[2:17], v[132:135], v[194:197], v[2:17]
	v_mfma_f32_32x32x16_bf16 v[2:17], v[136:139], v[208:211], v[2:17]
	s_cbranch_scc1 .LBB0_695
; __device__ __forceinline__ void bias_tile(f32x16& p0, f32x16& p1, int dq, const float* tb) {
; #pragma unroll
;     for (int r = 0; r < 16; ++r) {
;         const int c = (r & 3) + 8 * (r >> 2);
;         int d0 = dq - c, d1 = dq - c - 32;
;         d0 = d0 < 0 ? 0 : (d0 > 127 ? 127 : d0); d1 = d1 < 0 ? 0 : (d1 > 127 ? 127 : d1);
;         p0[r] += tb[d0]; p1[r] += tb[d1];
;     }
; }
	v_add_u32_e32 v131, 0xffffffc1, v126
	v_lshl_add_u32 v131, v131, 2, s33
	ds_read2_b32 v[208:209], v131 offset0:37 offset1:36
	ds_read2_b32 v[194:195], v131 offset0:39 offset1:38
	ds_read2_b32 v[190:191], v131 offset0:45 offset1:44
	ds_read2_b32 v[186:187], v131 offset0:47 offset1:46
	ds_read2_b32 v[182:183], v131 offset0:53 offset1:52
	ds_read2_b32 v[138:139], v131 offset0:55 offset1:54
	ds_read2_b32 v[134:135], v131 offset0:61 offset1:60
	ds_read2_b32 v[128:129], v131 offset0:63 offset1:62
	ds_read2_b32 v[210:211], v131 offset0:5 offset1:4
	ds_read2_b32 v[196:197], v131 offset0:7 offset1:6
	ds_read2_b32 v[192:193], v131 offset0:13 offset1:12
	ds_read2_b32 v[188:189], v131 offset0:15 offset1:14
	ds_read2_b32 v[184:185], v131 offset0:21 offset1:20
	ds_read2_b32 v[140:141], v131 offset0:23 offset1:22
	ds_read2_b32 v[136:137], v131 offset0:29 offset1:28
	ds_read2_b32 v[132:133], v131 offset0:31 offset1:30
	s_waitcnt lgkmcnt(0)
	v_pk_add_f32 v[96:97], v[96:97], v[208:209]
	v_pk_add_f32 v[94:95], v[94:95], v[194:195]
	v_pk_add_f32 v[92:93], v[92:93], v[190:191]
	v_pk_add_f32 v[90:91], v[90:91], v[186:187]
	v_pk_add_f32 v[88:89], v[88:89], v[182:183]
	v_pk_add_f32 v[86:87], v[86:87], v[138:139]
	v_pk_add_f32 v[84:85], v[84:85], v[134:135]
	v_pk_add_f32 v[82:83], v[82:83], v[128:129]
	v_pk_add_f32 v[80:81], v[80:81], v[210:211]
	v_pk_add_f32 v[78:79], v[78:79], v[196:197]
	v_pk_add_f32 v[76:77], v[76:77], v[192:193]
	v_pk_add_f32 v[74:75], v[74:75], v[188:189]
	v_pk_add_f32 v[72:73], v[72:73], v[184:185]
	v_pk_add_f32 v[70:71], v[70:71], v[140:141]
	v_pk_add_f32 v[68:69], v[68:69], v[136:137]
	v_pk_add_f32 v[66:67], v[66:67], v[132:133]

; __device__ __forceinline__ void bias_tile(f32x16& p0, f32x16& p1, int dq, const float* tb) {
; #pragma unroll
;     for (int r = 0; r < 16; ++r) {
;         const int c = (r & 3) + 8 * (r >> 2);
;         int d0 = dq - c, d1 = dq - c - 32;
;         d0 = d0 < 0 ? 0 : (d0 > 127 ? 127 : d0); d1 = d1 < 0 ? 0 : (d1 > 127 ? 127 : d1);
;         p0[r] += tb[d0]; p1[r] += tb[d1];
;     }
; }
; template <int VB>
; __device__ __forceinline__ void pv_tile(f32x16* o, int vb0, bf16x8 pa0, bf16x8 pa1, bf16x8 pa2, bf16x8 pa3) {
;     ...
;     PV_D0(0); PV_D0(1); PV_D0(2); PV_D0(3);
;     ...
; }
.LBB0_703:
	ds_read_b64_tr_b16 v[146:147], v153 offset:0x4000
	ds_read_b64_tr_b16 v[148:149], v153 offset:0x4800
	ds_read_b64_tr_b16 v[186:187], v153 offset:0x5000
	ds_read_b64_tr_b16 v[188:189], v153 offset:0x5800
	ds_read_b64_tr_b16 v[190:191], v153 offset:0x6000
	ds_read_b64_tr_b16 v[192:193], v153 offset:0x6800
	ds_read_b64_tr_b16 v[194:195], v153 offset:0x7000
	ds_read_b64_tr_b16 v[196:197], v153 offset:0x7800
	s_waitcnt lgkmcnt(0)
	s_nop 0
	v_mfma_f32_32x32x16_bf16 v[50:65], v[126:129], v[146:149], v[50:65]
	ds_read_b64_tr_b16 v[146:147], v153 offset:0x4200
	ds_read_b64_tr_b16 v[148:149], v153 offset:0x4a00
	v_mfma_f32_32x32x16_bf16 v[50:65], v[130:133], v[186:189], v[50:65]
	ds_read_b64_tr_b16 v[186:187], v153 offset:0x5200
	ds_read_b64_tr_b16 v[188:189], v153 offset:0x5a00
	v_mfma_f32_32x32x16_bf16 v[50:65], v[138:141], v[190:193], v[50:65]
	ds_read_b64_tr_b16 v[190:191], v153 offset:0x6200
	ds_read_b64_tr_b16 v[192:193], v153 offset:0x6a00
	v_mfma_f32_32x32x16_bf16 v[50:65], v[134:137], v[194:197], v[50:65]
	ds_read_b64_tr_b16 v[194:195], v153 offset:0x7200
	ds_read_b64_tr_b16 v[196:197], v153 offset:0x7a00
	s_waitcnt lgkmcnt(0)
	v_mfma_f32_32x32x16_bf16 v[34:49], v[126:129], v[146:149], v[34:49]
	ds_read_b64_tr_b16 v[146:147], v153 offset:0x4400
	ds_read_b64_tr_b16 v[148:149], v153 offset:0x4c00
	v_mfma_f32_32x32x16_bf16 v[34:49], v[130:133], v[186:189], v[34:49]
	ds_read_b64_tr_b16 v[186:187], v153 offset:0x5400
	ds_read_b64_tr_b16 v[188:189], v153 offset:0x5c00
	v_mfma_f32_32x32x16_bf16 v[34:49], v[138:141], v[190:193], v[34:49]
	ds_read_b64_tr_b16 v[190:191], v153 offset:0x6400
	ds_read_b64_tr_b16 v[192:193], v153 offset:0x6c00
	v_mfma_f32_32x32x16_bf16 v[34:49], v[134:137], v[194:197], v[34:49]
	ds_read_b64_tr_b16 v[194:195], v153 offset:0x7400
	ds_read_b64_tr_b16 v[196:197], v153 offset:0x7c00
	s_waitcnt lgkmcnt(0)
	v_mfma_f32_32x32x16_bf16 v[18:33], v[126:129], v[146:149], v[18:33]
	ds_read_b64_tr_b16 v[146:147], v153 offset:0x4600
	ds_read_b64_tr_b16 v[148:149], v153 offset:0x4e00
	v_mfma_f32_32x32x16_bf16 v[18:33], v[130:133], v[186:189], v[18:33]
	ds_read_b64_tr_b16 v[186:187], v153 offset:0x5600
	ds_read_b64_tr_b16 v[188:189], v153 offset:0x5e00
	v_mfma_f32_32x32x16_bf16 v[18:33], v[138:141], v[190:193], v[18:33]
	ds_read_b64_tr_b16 v[190:191], v153 offset:0x6600
	ds_read_b64_tr_b16 v[192:193], v153 offset:0x6e00
	v_mfma_f32_32x32x16_bf16 v[18:33], v[134:137], v[194:197], v[18:33]
	ds_read_b64_tr_b16 v[194:195], v153 offset:0x7600
	ds_read_b64_tr_b16 v[196:197], v153 offset:0x7e00
	s_waitcnt lgkmcnt(0)
	v_mfma_f32_32x32x16_bf16 v[2:17], v[126:129], v[146:149], v[2:17]
	s_add_i32 s4, s21, 0x71
	s_cmp_le_i32 s4, s30
	v_add_u32_e32 v126, 27, v180
	v_mfma_f32_32x32x16_bf16 v[2:17], v[130:133], v[186:189], v[2:17]
	v_mfma_f32_32x32x16_bf16 v[2:17], v[138:141], v[190:193], v[2:17]
	v_mfma_f32_32x32x16_bf16 v[2:17], v[134:137], v[194:197], v[2:17]
	s_cbranch_scc1 .LBB0_705
	v_add_u32_e32 v127, 0xffffffc1, v126
	v_lshl_add_u32 v127, v127, 2, s33
	ds_read2_b32 v[196:197], v127 offset0:37 offset1:36
	ds_read2_b32 v[192:193], v127 offset0:39 offset1:38
	ds_read2_b32 v[188:189], v127 offset0:45 offset1:44
	ds_read2_b32 v[148:149], v127 offset0:47 offset1:46
	ds_read2_b32 v[140:141], v127 offset0:53 offset1:52
	ds_read2_b32 v[136:137], v127 offset0:55 offset1:54
	ds_read2_b32 v[132:133], v127 offset0:61 offset1:60
	ds_read2_b32 v[128:129], v127 offset0:63 offset1:62
	ds_read2_b32 v[208:209], v127 offset0:5 offset1:4
	ds_read2_b32 v[194:195], v127 offset0:7 offset1:6
	ds_read2_b32 v[190:191], v127 offset0:13 offset1:12
	ds_read2_b32 v[186:187], v127 offset0:15 offset1:14
	ds_read2_b32 v[146:147], v127 offset0:21 offset1:20
	ds_read2_b32 v[138:139], v127 offset0:23 offset1:22
	ds_read2_b32 v[134:135], v127 offset0:29 offset1:28
	ds_read2_b32 v[130:131], v127 offset0:31 offset1:30
	s_waitcnt lgkmcnt(0)
	v_pk_add_f32 v[96:97], v[96:97], v[196:197]
	v_pk_add_f32 v[94:95], v[94:95], v[192:193]
	v_pk_add_f32 v[92:93], v[92:93], v[188:189]
	v_pk_add_f32 v[90:91], v[90:91], v[148:149]
	v_pk_add_f32 v[88:89], v[88:89], v[140:141]
	v_pk_add_f32 v[86:87], v[86:87], v[136:137]
	v_pk_add_f32 v[84:85], v[84:85], v[132:133]
	v_pk_add_f32 v[82:83], v[82:83], v[128:129]
	v_pk_add_f32 v[80:81], v[80:81], v[208:209]
	v_pk_add_f32 v[78:79], v[78:79], v[194:195]
	v_pk_add_f32 v[76:77], v[76:77], v[190:191]
	v_pk_add_f32 v[74:75], v[74:75], v[186:187]
	v_pk_add_f32 v[72:73], v[72:73], v[146:147]
	v_pk_add_f32 v[70:71], v[70:71], v[138:139]
	v_pk_add_f32 v[68:69], v[68:69], v[134:135]
	v_pk_add_f32 v[66:67], v[66:67], v[130:131]
